# P12/P5a gamma-beta hoisted out of row loops, P5c P.V LDS reads software-pipelined, barrier closing P5c->p5d LDS WAR window
# speedup vs baseline: 1.0139x; 1.0047x over previous
; __device__ __forceinline__ float bflo(unsigned w) { return __uint_as_float(w << 16); }
; __device__ __forceinline__ float bfhi(unsigned w) { return __uint_as_float(w & 0xffff0000u); }
; __global__ void __launch_bounds__(NTHREADS, 2) fwd_kernel(Params P) {
;     ...
;     if (PHON(5)) for (int r = gw; r < MR; r += NGW) {
;         const bf16_t* zr = Z + (size_t)r * NZ + 1024;
;         float v[16]; float s = 0.f;
; #pragma unroll
;         for (int h = 0; h < 2; ++h) { const u32x4 w = *(const u32x4*)(zr + 8 * lane + 512 * h);
;             v[8 * h + 0] = bflo(w.x); v[8 * h + 1] = bfhi(w.x); v[8 * h + 2] = bflo(w.y); v[8 * h + 3] = bfhi(w.y); v[8 * h + 4] = bflo(w.z); v[8 * h + 5] = bfhi(w.z); v[8 * h + 6] = bflo(w.w); v[8 * h + 7] = bfhi(w.w); }
; #pragma unroll
;         for (int j = 0; j < 16; ++j) s += v[j];
;         const float mean = wave_sum(s) * (1.f / BW); float s2 = 0.f;
; #pragma unroll
;         for (int j = 0; j < 16; ++j) { v[j] -= mean; s2 += v[j] * v[j]; }
;         const float rstd = 1.0f / sqrtf(wave_sum(s2) * (1.f / BW) + LN_EPS);
; #pragma unroll
;         for (int h = 0; h < 2; ++h) {
;             const int c0 = 8 * lane + 512 * h; float o[8];
; #pragma unroll
;             for (int j = 0; j < 8; ++j) o[j] = v[8 * h + j] * rstd * P.in[I_GLNG][c0 + j] + P.in[I_GLNB][c0 + j];
.LBB0_570:
	s_cmpk_lt_i32 s30, 0x2080
	s_cselect_b64 s[0:1], -1, 0
	v_writelane_b32 v255, s0, 31
	s_cmpk_gt_i32 s30, 0x207f
	s_nop 0
	v_writelane_b32 v255, s1, 32
	s_cbranch_scc1 .LBB0_577
	v_mbcnt_hi_u32_b32 v0, -1, v179
	v_and_b32_e32 v2, 64, v0
	v_add_u32_e32 v2, 64, v2
	v_xor_b32_e32 v3, 1, v0
	v_cmp_lt_i32_e32 vcc, v3, v2
	v_readlane_b32 s8, v254, 0
	v_readlane_b32 s9, v254, 1
	v_cndmask_b32_e32 v3, v0, v3, vcc
	v_lshlrev_b32_e32 v9, 2, v3
	v_xor_b32_e32 v3, 2, v0
	v_cmp_lt_i32_e32 vcc, v3, v2
	v_readlane_b32 s10, v254, 2
	v_readlane_b32 s11, v254, 3
	v_cndmask_b32_e32 v3, v0, v3, vcc
	v_lshlrev_b32_e32 v26, 2, v3
	v_xor_b32_e32 v3, 4, v0
	v_cmp_lt_i32_e32 vcc, v3, v2
	v_readlane_b32 s12, v254, 4
	v_readlane_b32 s13, v254, 5
	v_cndmask_b32_e32 v3, v0, v3, vcc
	v_lshlrev_b32_e32 v27, 2, v3
	v_xor_b32_e32 v3, 8, v0
	v_cmp_lt_i32_e32 vcc, v3, v2
	v_readlane_b32 s14, v254, 6
	v_readlane_b32 s15, v254, 7
	v_cndmask_b32_e32 v3, v0, v3, vcc
	s_mov_b64 s[8:9], s[12:13]
	v_lshlrev_b32_e32 v28, 2, v3
	v_xor_b32_e32 v3, 16, v0
	s_mov_b64 s[10:11], s[14:15]
	v_cmp_lt_i32_e32 vcc, v3, v2
	s_add_u32 s2, s10, 0x4b10000
	s_addc_u32 s3, s11, 0
	v_cndmask_b32_e32 v3, v0, v3, vcc
	s_lshl_b64 s[0:1], s[30:31], 11
	v_lshlrev_b32_e32 v29, 2, v3
	v_xor_b32_e32 v3, 32, v0
	v_readlane_b32 s8, v254, 11
	s_add_u32 s6, s92, s0
	v_cmp_lt_i32_e32 vcc, v3, v2
	v_readlane_b32 s9, v254, 12
	v_readlane_b32 s14, v254, 17
	v_readlane_b32 s15, v254, 18
	v_readlane_b32 s16, v254, 19
	v_readlane_b32 s17, v254, 20
	v_readlane_b32 s18, v254, 21
	v_readlane_b32 s19, v254, 22
	v_readlane_b32 s20, v254, 23
	v_readlane_b32 s21, v254, 24
	s_addc_u32 s7, s93, s1
	s_ashr_i32 s37, s36, 31
	v_cndmask_b32_e32 v0, v0, v3, vcc
	v_readlane_b32 s10, v254, 13
	v_readlane_b32 s22, v254, 25
	v_readlane_b32 s23, v254, 26
	s_mov_b64 s[14:15], s[18:19]
	s_mov_b64 s[16:17], s[20:21]
	s_lshl_b64 s[8:9], s[36:37], 11
	s_mul_i32 s1, s30, 0x5800
	v_mov_b32_e32 v1, 0
	v_lshlrev_b32_e32 v30, 2, v0
	v_lshlrev_b32_e32 v0, 5, v237
	v_readlane_b32 s11, v254, 14
	s_mov_b64 s[18:19], s[22:23]
	s_mul_hi_i32 s0, s30, 0x5800
	s_add_u32 s10, s92, s1
	v_lshlrev_b32_e32 v8, 3, v237
	s_mov_b32 s5, 0
	v_lshl_add_u64 v[10:11], s[14:15], 0, v[0:1]
	v_lshl_add_u64 v[12:13], s[16:17], 0, v[0:1]
	v_mov_b32_e32 v177, v1
	s_addc_u32 s11, s93, s0
	s_mul_hi_i32 s16, s36, 0x5800
	s_mul_i32 s17, s36, 0x5800
	v_mov_b32_e32 v31, 0x3727c5ac
	s_mov_b32 s18, 0xf800000
	v_mov_b32_e32 v32, 0x260
	s_mov_b32 s19, s30
	v_readlane_b32 s12, v254, 15
	v_readlane_b32 s13, v254, 16
	global_load_dwordx4 v[60:63], v[12:13], off
	global_load_dwordx4 v[64:67], v[10:11], off
	global_load_dwordx4 v[68:71], v[10:11], off offset:16
	global_load_dwordx4 v[72:75], v[12:13], off offset:16
	global_load_dwordx4 v[76:79], v[12:13], off offset:2048
	global_load_dwordx4 v[80:83], v[10:11], off offset:2048
	global_load_dwordx4 v[84:87], v[10:11], off offset:2064
	global_load_dwordx4 v[88:91], v[12:13], off offset:2064
	s_waitcnt vmcnt(0)
	s_branch .LBB0_573

; __device__ __forceinline__ unsigned cvt_pk_bf16(float lo, float hi) { unsigned r; asm volatile("v_cvt_pk_bf16_f32 %0, %1, %2" : "=v"(r) : "v"(lo), "v"(hi)); return r; }
; __device__ __forceinline__ float bflo(unsigned w) { return __uint_as_float(w << 16); }
; __device__ __forceinline__ float bfhi(unsigned w) { return __uint_as_float(w & 0xffff0000u); }
; __global__ void __launch_bounds__(NTHREADS, 2) fwd_kernel(Params P) {
;     ...
;     if (PHON(5)) for (int r = gw; r < MR; r += NGW) {
;         const bf16_t* zr = Z + (size_t)r * NZ + 1024;
;         float v[16]; float s = 0.f;
; #pragma unroll
;         for (int h = 0; h < 2; ++h) { const u32x4 w = *(const u32x4*)(zr + 8 * lane + 512 * h);
;             v[8 * h + 0] = bflo(w.x); v[8 * h + 1] = bfhi(w.x); v[8 * h + 2] = bflo(w.y); v[8 * h + 3] = bfhi(w.y); v[8 * h + 4] = bflo(w.z); v[8 * h + 5] = bfhi(w.z); v[8 * h + 6] = bflo(w.w); v[8 * h + 7] = bfhi(w.w); }
; #pragma unroll
;         for (int j = 0; j < 16; ++j) s += v[j];
;         const float mean = wave_sum(s) * (1.f / BW); float s2 = 0.f;
; #pragma unroll
;         for (int j = 0; j < 16; ++j) { v[j] -= mean; s2 += v[j] * v[j]; }
;         const float rstd = 1.0f / sqrtf(wave_sum(s2) * (1.f / BW) + LN_EPS);
; #pragma unroll
;         for (int h = 0; h < 2; ++h) {
;             const int c0 = 8 * lane + 512 * h; float o[8];
; #pragma unroll
;             for (int j = 0; j < 8; ++j) o[j] = v[8 * h + j] * rstd * P.in[I_GLNG][c0 + j] + P.in[I_GLNB][c0 + j];
;             u32x4 w; w.x = cvt_pk_bf16(o[0], o[1]); w.y = cvt_pk_bf16(o[2], o[3]); w.z = cvt_pk_bf16(o[4], o[5]); w.w = cvt_pk_bf16(o[6], o[7]);
;             *(u32x4*)(VP + (size_t)r * BW + c0) = w;
;             if (r >= MP) { float* ov = out + O_VS + (size_t)(r - MP) * BW + c0; *(f32x4*)ov = (f32x4){o[0], o[1], o[2], o[3]}; *(f32x4*)(ov + 4) = (f32x4){o[4], o[5], o[6], o[7]}; }
.LBB0_573:
	v_lshl_add_u64 v[0:1], s[10:11], 0, v[176:177]
	v_add_co_u32_e32 v4, vcc, 0xeda0000, v0
	s_cmpk_gt_i32 s19, 0x1fff
	s_nop 0
	v_addc_co_u32_e32 v5, vcc, 0, v1, vcc
	global_load_dwordx4 v[0:3], v[4:5], off offset:3072
	s_nop 0
	global_load_dwordx4 v[4:7], v[4:5], off offset:2048
	s_cselect_b64 s[14:15], -1, 0
	s_add_i32 s4, s19, 0xffffe000
	s_lshl_b64 s[0:1], s[4:5], 12
	s_add_u32 s12, s2, s0
	s_addc_u32 s13, s3, s1
	s_cmpk_lt_i32 s19, 0x2000
	s_waitcnt vmcnt(1)
	v_lshlrev_b32_e32 v14, 16, v0
	s_waitcnt vmcnt(0)
	v_lshlrev_b32_e32 v22, 16, v4
	v_and_b32_e32 v15, 0xffff0000, v0
	v_and_b32_e32 v23, 0xffff0000, v4
	v_add_f32_e32 v0, 0, v22
	v_lshlrev_b32_e32 v4, 16, v5
	v_add_f32_e32 v0, v0, v23
	v_and_b32_e32 v5, 0xffff0000, v5
	v_add_f32_e32 v0, v0, v4
	v_lshlrev_b32_e32 v24, 16, v6
	v_add_f32_e32 v0, v0, v5
	v_and_b32_e32 v25, 0xffff0000, v6
	v_add_f32_e32 v0, v0, v24
	v_lshlrev_b32_e32 v6, 16, v7
	v_add_f32_e32 v0, v0, v25
	v_and_b32_e32 v7, 0xffff0000, v7
	v_add_f32_e32 v0, v0, v6
	v_add_f32_e32 v0, v0, v7
	v_add_f32_e32 v0, v0, v14
	v_lshlrev_b32_e32 v16, 16, v1
	v_add_f32_e32 v0, v0, v15
	v_and_b32_e32 v17, 0xffff0000, v1
	v_add_f32_e32 v0, v0, v16
	v_lshlrev_b32_e32 v18, 16, v2
	v_add_f32_e32 v0, v0, v17
	v_and_b32_e32 v19, 0xffff0000, v2
	v_add_f32_e32 v0, v0, v18
	v_lshlrev_b32_e32 v20, 16, v3
	v_add_f32_e32 v0, v0, v19
	v_and_b32_e32 v21, 0xffff0000, v3
	v_add_f32_e32 v0, v0, v20
	v_add_f32_e32 v0, v0, v21
	ds_bpermute_b32 v1, v9, v0
	s_waitcnt lgkmcnt(0)
	v_add_f32_e32 v0, v0, v1
	ds_bpermute_b32 v1, v26, v0
	s_waitcnt lgkmcnt(0)
	v_add_f32_e32 v0, v0, v1
	ds_bpermute_b32 v1, v27, v0
	s_waitcnt lgkmcnt(0)
	v_add_f32_e32 v0, v0, v1
	ds_bpermute_b32 v1, v28, v0
	s_waitcnt lgkmcnt(0)
	v_add_f32_e32 v0, v0, v1
	ds_bpermute_b32 v1, v29, v0
	s_waitcnt lgkmcnt(0)
	v_add_f32_e32 v33, v0, v1
	ds_bpermute_b32 v34, v30, v33
	v_mov_b32_e32 v0, v60
	v_mov_b32_e32 v1, v61
	v_mov_b32_e32 v2, v62
	v_mov_b32_e32 v3, v63
	s_waitcnt lgkmcnt(0)
	v_add_f32_e32 v33, v33, v34
	v_mul_f32_e32 v34, 0x3a800000, v33
	v_pk_add_f32 v[42:43], v[22:23], v[34:35] op_sel_hi:[1,0] neg_lo:[0,1] neg_hi:[0,1]
	v_pk_add_f32 v[44:45], v[4:5], v[34:35] op_sel_hi:[1,0] neg_lo:[0,1] neg_hi:[0,1]
	v_pk_mul_f32 v[4:5], v[42:43], v[42:43]
	v_pk_add_f32 v[48:49], v[6:7], v[34:35] op_sel_hi:[1,0] neg_lo:[0,1] neg_hi:[0,1]
	v_pk_mul_f32 v[6:7], v[44:45], v[44:45]
	v_add_f32_e32 v4, v4, v5
	v_pk_add_f32 v[46:47], v[24:25], v[34:35] op_sel_hi:[1,0] neg_lo:[0,1] neg_hi:[0,1]
	v_add_f32_e32 v4, v4, v6
	v_pk_mul_f32 v[22:23], v[46:47], v[46:47]
	v_add_f32_e32 v4, v4, v7
	v_add_f32_e32 v4, v4, v22
	v_pk_mul_f32 v[24:25], v[48:49], v[48:49]
	v_add_f32_e32 v4, v4, v23
	v_pk_add_f32 v[14:15], v[14:15], v[34:35] op_sel_hi:[1,0] neg_lo:[0,1] neg_hi:[0,1]
	v_add_f32_e32 v4, v4, v24
	v_pk_add_f32 v[16:17], v[16:17], v[34:35] op_sel_hi:[1,0] neg_lo:[0,1] neg_hi:[0,1]
	v_pk_add_f32 v[18:19], v[18:19], v[34:35] op_sel_hi:[1,0] neg_lo:[0,1] neg_hi:[0,1]
	v_pk_add_f32 v[20:21], v[20:21], v[34:35] op_sel_hi:[1,0] neg_lo:[0,1] neg_hi:[0,1]
	v_pk_mul_f32 v[34:35], v[14:15], v[14:15]
	v_add_f32_e32 v4, v4, v25
	v_add_f32_e32 v4, v4, v34
	v_pk_mul_f32 v[36:37], v[16:17], v[16:17]
	v_add_f32_e32 v4, v4, v35
	v_add_f32_e32 v4, v4, v36
	v_pk_mul_f32 v[38:39], v[18:19], v[18:19]
	v_add_f32_e32 v4, v4, v37
	v_add_f32_e32 v4, v4, v38
	v_pk_mul_f32 v[40:41], v[20:21], v[20:21]
	v_add_f32_e32 v4, v4, v39
	v_add_f32_e32 v4, v4, v40
	v_add_f32_e32 v22, v4, v41
	v_mov_b32_e32 v4, v64
	v_mov_b32_e32 v5, v65
	v_mov_b32_e32 v6, v66
	v_mov_b32_e32 v7, v67
	v_mov_b32_e32 v34, v68
	v_mov_b32_e32 v35, v69
	v_mov_b32_e32 v36, v70
	v_mov_b32_e32 v37, v71
	v_mov_b32_e32 v38, v72
	v_mov_b32_e32 v39, v73
	v_mov_b32_e32 v40, v74
	v_mov_b32_e32 v41, v75
	ds_bpermute_b32 v23, v9, v22
	s_waitcnt lgkmcnt(0)
	v_add_f32_e32 v22, v22, v23
	ds_bpermute_b32 v23, v26, v22
	s_waitcnt lgkmcnt(0)
	v_add_f32_e32 v22, v22, v23
	ds_bpermute_b32 v23, v27, v22
	s_waitcnt lgkmcnt(0)
	v_add_f32_e32 v22, v22, v23
	ds_bpermute_b32 v23, v28, v22
	s_waitcnt lgkmcnt(0)
	v_add_f32_e32 v22, v22, v23
	ds_bpermute_b32 v23, v29, v22
	s_waitcnt lgkmcnt(0)
	v_add_f32_e32 v24, v22, v23
	ds_bpermute_b32 v25, v30, v24
	v_lshl_add_u64 v[22:23], s[6:7], 0, v[176:177]
	s_waitcnt lgkmcnt(0)
	v_add_f32_e32 v24, v24, v25
	v_fmamk_f32 v24, v24, 0x3a800000, v31
	v_mul_f32_e32 v25, 0x4f800000, v24
	v_cmp_gt_f32_e32 vcc, s18, v24
	s_nop 1
	v_cndmask_b32_e32 v24, v24, v25, vcc
	v_sqrt_f32_e32 v25, v24
	s_nop 0
	v_add_u32_e32 v33, -1, v25
	v_add_u32_e32 v50, 1, v25
	v_fma_f32 v51, -v33, v25, v24
	v_fma_f32 v52, -v50, v25, v24
	v_cmp_ge_f32_e64 s[0:1], 0, v51
	s_nop 1
	v_cndmask_b32_e64 v25, v25, v33, s[0:1]
	v_cmp_lt_f32_e64 s[0:1], 0, v52
	s_nop 1
	v_cndmask_b32_e64 v25, v25, v50, s[0:1]
	v_mul_f32_e32 v33, 0x37800000, v25
	v_cndmask_b32_e32 v25, v25, v33, vcc
	v_cmp_class_f32_e32 vcc, v24, v32
	s_nop 1
	v_cndmask_b32_e32 v24, v25, v24, vcc
	v_div_scale_f32 v25, s[0:1], v24, v24, 1.0
	v_rcp_f32_e32 v33, v25
	v_div_scale_f32 v50, vcc, 1.0, v24, 1.0
	v_fma_f32 v51, -v25, v33, 1.0
	v_fmac_f32_e32 v33, v51, v33
	v_mul_f32_e32 v51, v50, v33
	v_fma_f32 v52, -v25, v51, v50
	v_fmac_f32_e32 v51, v52, v33
	v_fma_f32 v25, -v25, v51, v50
	v_div_fmas_f32 v25, v25, v33, v51
	v_div_fixup_f32 v24, v25, v24, 1.0
	v_add_co_u32_e32 v50, vcc, 0x22720000, v22
	v_pk_mul_f32 v[42:43], v[24:25], v[42:43] op_sel_hi:[0,1]
	v_pk_mul_f32 v[44:45], v[24:25], v[44:45] op_sel_hi:[0,1]
	v_pk_mul_f32 v[46:47], v[24:25], v[46:47] op_sel_hi:[0,1]
	v_pk_mul_f32 v[48:49], v[24:25], v[48:49] op_sel_hi:[0,1]
	v_addc_co_u32_e32 v51, vcc, 0, v23, vcc
	v_pk_fma_f32 v[4:5], v[42:43], v[4:5], v[0:1]
	v_pk_fma_f32 v[6:7], v[44:45], v[6:7], v[2:3]
	v_pk_fma_f32 v[0:1], v[46:47], v[34:35], v[38:39]
	v_pk_fma_f32 v[2:3], v[48:49], v[36:37], v[40:41]
	v_lshlrev_b32_e32 v33, 2, v8
	v_cvt_pk_bf16_f32 v34, v4, v5
	v_cvt_pk_bf16_f32 v35, v6, v7
	v_cvt_pk_bf16_f32 v36, v0, v1
	v_cvt_pk_bf16_f32 v37, v2, v3
	global_store_dwordx4 v[50:51], v[34:37], off
	s_cbranch_scc1 .LBB0_575
	global_store_dwordx4 v33, v[4:7], s[12:13]
	global_store_dwordx4 v33, v[0:3], s[12:13] offset:16
; __device__ __forceinline__ unsigned cvt_pk_bf16(float lo, float hi) { unsigned r; asm volatile("v_cvt_pk_bf16_f32 %0, %1, %2" : "=v"(r) : "v"(lo), "v"(hi)); return r; }
; __global__ void __launch_bounds__(NTHREADS, 2) fwd_kernel(Params P) {
;     ...
;         for (int h = 0; h < 2; ++h) {
;             const int c0 = 8 * lane + 512 * h; float o[8];
; #pragma unroll
;             for (int j = 0; j < 8; ++j) o[j] = v[8 * h + j] * rstd * P.in[I_GLNG][c0 + j] + P.in[I_GLNB][c0 + j];
;             u32x4 w; w.x = cvt_pk_bf16(o[0], o[1]); w.y = cvt_pk_bf16(o[2], o[3]); w.z = cvt_pk_bf16(o[4], o[5]); w.w = cvt_pk_bf16(o[6], o[7]);
;             *(u32x4*)(VP + (size_t)r * BW + c0) = w;
;             if (r >= MP) { float* ov = out + O_VS + (size_t)(r - MP) * BW + c0; *(f32x4*)ov = (f32x4){o[0], o[1], o[2], o[3]}; *(f32x4*)(ov + 4) = (f32x4){o[4], o[5], o[6], o[7]}; }
.LBB0_575:
	s_nop 1
	v_mov_b32_e32 v0, v76
	v_mov_b32_e32 v1, v77
	v_mov_b32_e32 v2, v78
	v_mov_b32_e32 v3, v79
	s_nop 0
	v_mov_b32_e32 v4, v80
	v_mov_b32_e32 v5, v81
	v_mov_b32_e32 v6, v82
	v_mov_b32_e32 v7, v83
	v_mov_b32_e32 v34, v84
	v_mov_b32_e32 v35, v85
	v_mov_b32_e32 v36, v86
	v_mov_b32_e32 v37, v87
	v_mov_b32_e32 v38, v88
	v_mov_b32_e32 v39, v89
	v_mov_b32_e32 v40, v90
	v_mov_b32_e32 v41, v91
	v_mov_b32_e32 v25, v24
	v_add_co_u32_e32 v22, vcc, 0x22720000, v22
	v_pk_mul_f32 v[14:15], v[24:25], v[14:15]
	v_pk_mul_f32 v[16:17], v[24:25], v[16:17]
	v_pk_mul_f32 v[18:19], v[24:25], v[18:19]
	v_pk_mul_f32 v[20:21], v[24:25], v[20:21]
	v_addc_co_u32_e32 v23, vcc, 0, v23, vcc
	s_andn2_b64 vcc, exec, s[14:15]
	v_pk_fma_f32 v[4:5], v[14:15], v[4:5], v[0:1]
	v_pk_fma_f32 v[6:7], v[16:17], v[6:7], v[2:3]
	v_pk_fma_f32 v[0:1], v[18:19], v[34:35], v[38:39]
	v_pk_fma_f32 v[2:3], v[20:21], v[36:37], v[40:41]
	v_cvt_pk_bf16_f32 v14, v4, v5
	v_cvt_pk_bf16_f32 v15, v6, v7
	v_cvt_pk_bf16_f32 v16, v0, v1
	s_nop 0
	v_cvt_pk_bf16_f32 v17, v2, v3
	global_store_dwordx4 v[22:23], v[14:17], off offset:1024
	s_cbranch_vccnz .LBB0_572
	global_store_dwordx4 v33, v[4:7], s[12:13] offset:2048
	global_store_dwordx4 v33, v[0:3], s[12:13] offset:2064
	s_branch .LBB0_572

; #define LAS __attribute__((address_space(3)))
; __device__ __forceinline__ unsigned cvt_pk_bf16(float lo, float hi) { unsigned r; asm volatile("v_cvt_pk_bf16_f32 %0, %1, %2" : "=v"(r) : "v"(lo), "v"(hi)); return r; }
; __global__ void __launch_bounds__(NTHREADS, 2) fwd_kernel(Params P) {
;     ...
;         for (int dt = 0; dt < 16; ++dt) {
;             f32x4 o = (f32x4){0.f, 0.f, 0.f, 0.f};
; #pragma unroll
;             for (int ks = 0; ks < 8; ++ks) {
;                 const LAS bf16_t* vp = KL + (dt * 16 + fr) * 264 + ks * 32 + 4 * fq;
;                 const u32x2 lo = *(const LAS u32x2*)vp, hi = *(const LAS u32x2*)(vp + 16);
;                 const u32x4 w = (u32x4){lo.x, lo.y, hi.x, hi.y};
;                 o = __builtin_amdgcn_mfma_f32_16x16x32_bf16(__builtin_bit_cast(bf16x8, w), pf[ks], o, 0, 0, 0);
;             }
;             u32x2 w; w.x = cvt_pk_bf16(o[0] * inv, o[1] * inv); w.y = cvt_pk_bf16(o[2] * inv, o[3] * inv);
;             *(u32x2*)(YS + (size_t)(row0 + fr) * 3072 + 2048 + h * HD + dt * 16 + 4 * fq) = w;
;         }
.LBB0_629:
	v_add_u32_e32 v250, 0x0, v35
	ds_read2_b64 v[44:47], v250 offset1:4
	ds_read2_b64 v[226:229], v250 offset0:8 offset1:12
	ds_read2_b64 v[230:233], v250 offset0:16 offset1:20
	ds_read2_b64 v[238:241], v250 offset0:24 offset1:28
	ds_read2_b64 v[242:245], v250 offset0:32 offset1:36
	ds_read2_b64 v[246:249], v250 offset0:40 offset1:44
	s_waitcnt lgkmcnt(5)
	v_mfma_f32_16x16x32_bf16 v[36:39], v[44:47], v[0:3], 0
	ds_read2_b64 v[44:47], v250 offset0:48 offset1:52
	s_waitcnt lgkmcnt(5)
	v_mfma_f32_16x16x32_bf16 v[36:39], v[226:229], v[4:7], v[36:39]
	ds_read2_b64 v[226:229], v250 offset0:56 offset1:60
	s_waitcnt lgkmcnt(5)
	v_mfma_f32_16x16x32_bf16 v[36:39], v[230:233], v[8:11], v[36:39]
	v_add_u32_e32 v251, 0x2100, v35
	ds_read2_b64 v[230:233], v251 offset1:4
	s_waitcnt lgkmcnt(5)
	v_mfma_f32_16x16x32_bf16 v[36:39], v[238:241], v[12:15], v[36:39]
	ds_read2_b64 v[238:241], v251 offset0:8 offset1:12
	s_waitcnt lgkmcnt(5)
	v_mfma_f32_16x16x32_bf16 v[36:39], v[242:245], v[16:19], v[36:39]
	ds_read2_b64 v[242:245], v251 offset0:16 offset1:20
	s_waitcnt lgkmcnt(5)
	v_mfma_f32_16x16x32_bf16 v[36:39], v[246:249], v[20:23], v[36:39]
	ds_read2_b64 v[246:249], v251 offset0:24 offset1:28
	s_waitcnt lgkmcnt(5)
	v_mfma_f32_16x16x32_bf16 v[36:39], v[44:47], v[24:27], v[36:39]
	ds_read2_b64 v[44:47], v251 offset0:32 offset1:36
	s_waitcnt lgkmcnt(5)
	v_mfma_f32_16x16x32_bf16 v[36:39], v[226:229], v[28:31], v[36:39]
	ds_read2_b64 v[226:229], v251 offset0:40 offset1:44
	s_waitcnt lgkmcnt(5)
	v_mfma_f32_16x16x32_bf16 v[40:43], v[230:233], v[0:3], 0
	ds_read2_b64 v[230:233], v251 offset0:48 offset1:52
	s_waitcnt lgkmcnt(5)
	v_mfma_f32_16x16x32_bf16 v[40:43], v[238:241], v[4:7], v[40:43]
	ds_read2_b64 v[238:241], v251 offset0:56 offset1:60
	s_nop 1
	v_mul_f32_e32 v36, v34, v36
	v_mul_f32_e32 v37, v34, v37
	v_mul_f32_e32 v38, v34, v38
	v_mul_f32_e32 v39, v34, v39
	v_cvt_pk_bf16_f32 v48, v36, v37
	v_cvt_pk_bf16_f32 v49, v38, v39
	global_store_dwordx2 v[32:33], v[48:49], off offset:-64
	s_waitcnt lgkmcnt(5)
	v_mfma_f32_16x16x32_bf16 v[40:43], v[242:245], v[8:11], v[40:43]
	v_add_u32_e32 v250, 0x4200, v35
	ds_read2_b64 v[242:245], v250 offset1:4
	s_waitcnt lgkmcnt(5)
	v_mfma_f32_16x16x32_bf16 v[40:43], v[246:249], v[12:15], v[40:43]
	ds_read2_b64 v[246:249], v250 offset0:8 offset1:12
	s_waitcnt lgkmcnt(5)
	v_mfma_f32_16x16x32_bf16 v[40:43], v[44:47], v[16:19], v[40:43]
	ds_read2_b64 v[44:47], v250 offset0:16 offset1:20
	s_waitcnt lgkmcnt(5)
	v_mfma_f32_16x16x32_bf16 v[40:43], v[226:229], v[20:23], v[40:43]
	ds_read2_b64 v[226:229], v250 offset0:24 offset1:28
	s_waitcnt lgkmcnt(5)
	v_mfma_f32_16x16x32_bf16 v[40:43], v[230:233], v[24:27], v[40:43]
	ds_read2_b64 v[230:233], v250 offset0:32 offset1:36
	s_waitcnt lgkmcnt(5)
	v_mfma_f32_16x16x32_bf16 v[40:43], v[238:241], v[28:31], v[40:43]
	ds_read2_b64 v[238:241], v250 offset0:40 offset1:44
	s_waitcnt lgkmcnt(5)
	v_mfma_f32_16x16x32_bf16 v[36:39], v[242:245], v[0:3], 0
	ds_read2_b64 v[242:245], v250 offset0:48 offset1:52
	s_waitcnt lgkmcnt(5)
	v_mfma_f32_16x16x32_bf16 v[36:39], v[246:249], v[4:7], v[36:39]
	ds_read2_b64 v[246:249], v250 offset0:56 offset1:60
	s_nop 1
	v_mul_f32_e32 v40, v34, v40
	v_mul_f32_e32 v41, v34, v41
	v_mul_f32_e32 v42, v34, v42
	v_mul_f32_e32 v43, v34, v43
	v_cvt_pk_bf16_f32 v252, v40, v41
	v_cvt_pk_bf16_f32 v253, v42, v43
	global_store_dwordx2 v[32:33], v[252:253], off offset:-32
	s_waitcnt lgkmcnt(5)
	v_mfma_f32_16x16x32_bf16 v[36:39], v[44:47], v[8:11], v[36:39]
	v_add_u32_e32 v251, 0x6300, v35
	ds_read2_b64 v[44:47], v251 offset1:4
	s_waitcnt lgkmcnt(5)
	v_mfma_f32_16x16x32_bf16 v[36:39], v[226:229], v[12:15], v[36:39]
	ds_read2_b64 v[226:229], v251 offset0:8 offset1:12
	s_waitcnt lgkmcnt(5)
	v_mfma_f32_16x16x32_bf16 v[36:39], v[230:233], v[16:19], v[36:39]
	ds_read2_b64 v[230:233], v251 offset0:16 offset1:20
	s_waitcnt lgkmcnt(5)
	v_mfma_f32_16x16x32_bf16 v[36:39], v[238:241], v[20:23], v[36:39]
	ds_read2_b64 v[238:241], v251 offset0:24 offset1:28
	s_waitcnt lgkmcnt(5)
	v_mfma_f32_16x16x32_bf16 v[36:39], v[242:245], v[24:27], v[36:39]
	ds_read2_b64 v[242:245], v251 offset0:32 offset1:36
	s_waitcnt lgkmcnt(5)
	v_mfma_f32_16x16x32_bf16 v[36:39], v[246:249], v[28:31], v[36:39]
	ds_read2_b64 v[246:249], v251 offset0:40 offset1:44
	s_waitcnt lgkmcnt(5)
	v_mfma_f32_16x16x32_bf16 v[40:43], v[44:47], v[0:3], 0
	ds_read2_b64 v[44:47], v251 offset0:48 offset1:52
	s_waitcnt lgkmcnt(5)
	v_mfma_f32_16x16x32_bf16 v[40:43], v[226:229], v[4:7], v[40:43]
	ds_read2_b64 v[226:229], v251 offset0:56 offset1:60
	s_nop 1
	v_mul_f32_e32 v36, v34, v36
	v_mul_f32_e32 v37, v34, v37
	v_mul_f32_e32 v38, v34, v38
	v_mul_f32_e32 v39, v34, v39
	v_cvt_pk_bf16_f32 v48, v36, v37
	v_cvt_pk_bf16_f32 v49, v38, v39
	global_store_dwordx2 v[32:33], v[48:49], off
	s_waitcnt lgkmcnt(5)
	v_mfma_f32_16x16x32_bf16 v[40:43], v[230:233], v[8:11], v[40:43]
	v_add_u32_e32 v250, 0x8400, v35
	ds_read2_b64 v[230:233], v250 offset1:4
	s_waitcnt lgkmcnt(5)
	v_mfma_f32_16x16x32_bf16 v[40:43], v[238:241], v[12:15], v[40:43]
	ds_read2_b64 v[238:241], v250 offset0:8 offset1:12
	s_waitcnt lgkmcnt(5)
	v_mfma_f32_16x16x32_bf16 v[40:43], v[242:245], v[16:19], v[40:43]
	ds_read2_b64 v[242:245], v250 offset0:16 offset1:20
	s_waitcnt lgkmcnt(5)
	v_mfma_f32_16x16x32_bf16 v[40:43], v[246:249], v[20:23], v[40:43]
	ds_read2_b64 v[246:249], v250 offset0:24 offset1:28
	s_waitcnt lgkmcnt(5)
	v_mfma_f32_16x16x32_bf16 v[40:43], v[44:47], v[24:27], v[40:43]
	ds_read2_b64 v[44:47], v250 offset0:32 offset1:36
	s_waitcnt lgkmcnt(5)
	v_mfma_f32_16x16x32_bf16 v[40:43], v[226:229], v[28:31], v[40:43]
	ds_read2_b64 v[226:229], v250 offset0:40 offset1:44
	s_waitcnt lgkmcnt(5)
; #define LAS __attribute__((address_space(3)))
; __device__ __forceinline__ unsigned cvt_pk_bf16(float lo, float hi) { unsigned r; asm volatile("v_cvt_pk_bf16_f32 %0, %1, %2" : "=v"(r) : "v"(lo), "v"(hi)); return r; }
; __global__ void __launch_bounds__(NTHREADS, 2) fwd_kernel(Params P) {
;     ...
;         for (int dt = 0; dt < 16; ++dt) {
;             f32x4 o = (f32x4){0.f, 0.f, 0.f, 0.f};
; #pragma unroll
;             for (int ks = 0; ks < 8; ++ks) {
;                 const LAS bf16_t* vp = KL + (dt * 16 + fr) * 264 + ks * 32 + 4 * fq;
;                 const u32x2 lo = *(const LAS u32x2*)vp, hi = *(const LAS u32x2*)(vp + 16);
;                 const u32x4 w = (u32x4){lo.x, lo.y, hi.x, hi.y};
;                 o = __builtin_amdgcn_mfma_f32_16x16x32_bf16(__builtin_bit_cast(bf16x8, w), pf[ks], o, 0, 0, 0);
;             }
;             u32x2 w; w.x = cvt_pk_bf16(o[0] * inv, o[1] * inv); w.y = cvt_pk_bf16(o[2] * inv, o[3] * inv);
;             *(u32x2*)(YS + (size_t)(row0 + fr) * 3072 + 2048 + h * HD + dt * 16 + 4 * fq) = w;
;         }
	v_mfma_f32_16x16x32_bf16 v[36:39], v[230:233], v[0:3], 0
	ds_read2_b64 v[230:233], v250 offset0:48 offset1:52
	s_waitcnt lgkmcnt(5)
	v_mfma_f32_16x16x32_bf16 v[36:39], v[238:241], v[4:7], v[36:39]
	ds_read2_b64 v[238:241], v250 offset0:56 offset1:60
	s_nop 1
	v_mul_f32_e32 v40, v34, v40
	v_mul_f32_e32 v41, v34, v41
	v_mul_f32_e32 v42, v34, v42
	v_mul_f32_e32 v43, v34, v43
	v_cvt_pk_bf16_f32 v252, v40, v41
	v_cvt_pk_bf16_f32 v253, v42, v43
	global_store_dwordx2 v[32:33], v[252:253], off offset:32
	s_waitcnt lgkmcnt(5)
	v_mfma_f32_16x16x32_bf16 v[36:39], v[242:245], v[8:11], v[36:39]
	v_add_u32_e32 v251, 0xa500, v35
	ds_read2_b64 v[242:245], v251 offset1:4
	s_waitcnt lgkmcnt(5)
	v_mfma_f32_16x16x32_bf16 v[36:39], v[246:249], v[12:15], v[36:39]
	ds_read2_b64 v[246:249], v251 offset0:8 offset1:12
	s_waitcnt lgkmcnt(5)
	v_mfma_f32_16x16x32_bf16 v[36:39], v[44:47], v[16:19], v[36:39]
	ds_read2_b64 v[44:47], v251 offset0:16 offset1:20
	s_waitcnt lgkmcnt(5)
	v_mfma_f32_16x16x32_bf16 v[36:39], v[226:229], v[20:23], v[36:39]
	ds_read2_b64 v[226:229], v251 offset0:24 offset1:28
	s_waitcnt lgkmcnt(5)
	v_mfma_f32_16x16x32_bf16 v[36:39], v[230:233], v[24:27], v[36:39]
	ds_read2_b64 v[230:233], v251 offset0:32 offset1:36
	s_waitcnt lgkmcnt(5)
	v_mfma_f32_16x16x32_bf16 v[36:39], v[238:241], v[28:31], v[36:39]
	ds_read2_b64 v[238:241], v251 offset0:40 offset1:44
	s_waitcnt lgkmcnt(5)
	v_mfma_f32_16x16x32_bf16 v[40:43], v[242:245], v[0:3], 0
	ds_read2_b64 v[242:245], v251 offset0:48 offset1:52
	s_waitcnt lgkmcnt(5)
	v_mfma_f32_16x16x32_bf16 v[40:43], v[246:249], v[4:7], v[40:43]
	ds_read2_b64 v[246:249], v251 offset0:56 offset1:60
	s_nop 1
	v_mul_f32_e32 v36, v34, v36
	v_mul_f32_e32 v37, v34, v37
	v_mul_f32_e32 v38, v34, v38
	v_mul_f32_e32 v39, v34, v39
	v_cvt_pk_bf16_f32 v48, v36, v37
	v_cvt_pk_bf16_f32 v49, v38, v39
	global_store_dwordx2 v[32:33], v[48:49], off offset:64
	s_waitcnt lgkmcnt(5)
	v_mfma_f32_16x16x32_bf16 v[40:43], v[44:47], v[8:11], v[40:43]
	v_add_u32_e32 v250, 0xc600, v35
	ds_read2_b64 v[44:47], v250 offset1:4
	s_waitcnt lgkmcnt(5)
	v_mfma_f32_16x16x32_bf16 v[40:43], v[226:229], v[12:15], v[40:43]
	ds_read2_b64 v[226:229], v250 offset0:8 offset1:12
	s_waitcnt lgkmcnt(5)
	v_mfma_f32_16x16x32_bf16 v[40:43], v[230:233], v[16:19], v[40:43]
	ds_read2_b64 v[230:233], v250 offset0:16 offset1:20
	s_waitcnt lgkmcnt(5)
	v_mfma_f32_16x16x32_bf16 v[40:43], v[238:241], v[20:23], v[40:43]
	ds_read2_b64 v[238:241], v250 offset0:24 offset1:28
	s_waitcnt lgkmcnt(5)
	v_mfma_f32_16x16x32_bf16 v[40:43], v[242:245], v[24:27], v[40:43]
	ds_read2_b64 v[242:245], v250 offset0:32 offset1:36
	s_waitcnt lgkmcnt(5)
	v_mfma_f32_16x16x32_bf16 v[40:43], v[246:249], v[28:31], v[40:43]
	ds_read2_b64 v[246:249], v250 offset0:40 offset1:44
	s_waitcnt lgkmcnt(5)
	v_mfma_f32_16x16x32_bf16 v[36:39], v[44:47], v[0:3], 0
	ds_read2_b64 v[44:47], v250 offset0:48 offset1:52
	s_waitcnt lgkmcnt(5)
	v_mfma_f32_16x16x32_bf16 v[36:39], v[226:229], v[4:7], v[36:39]
	ds_read2_b64 v[226:229], v250 offset0:56 offset1:60
	s_nop 1
	v_mul_f32_e32 v40, v34, v40
	v_mul_f32_e32 v41, v34, v41
	v_mul_f32_e32 v42, v34, v42
	v_mul_f32_e32 v43, v34, v43
	v_cvt_pk_bf16_f32 v252, v40, v41
	v_cvt_pk_bf16_f32 v253, v42, v43
	global_store_dwordx2 v[32:33], v[252:253], off offset:96
	s_waitcnt lgkmcnt(5)
	v_mfma_f32_16x16x32_bf16 v[36:39], v[230:233], v[8:11], v[36:39]
	v_add_u32_e32 v251, 0xe700, v35
	ds_read2_b64 v[230:233], v251 offset1:4
	s_waitcnt lgkmcnt(5)
	v_mfma_f32_16x16x32_bf16 v[36:39], v[238:241], v[12:15], v[36:39]
	ds_read2_b64 v[238:241], v251 offset0:8 offset1:12
	s_waitcnt lgkmcnt(5)
	v_mfma_f32_16x16x32_bf16 v[36:39], v[242:245], v[16:19], v[36:39]
	ds_read2_b64 v[242:245], v251 offset0:16 offset1:20
	s_waitcnt lgkmcnt(5)
	v_mfma_f32_16x16x32_bf16 v[36:39], v[246:249], v[20:23], v[36:39]
	ds_read2_b64 v[246:249], v251 offset0:24 offset1:28
	s_waitcnt lgkmcnt(5)
	v_mfma_f32_16x16x32_bf16 v[36:39], v[44:47], v[24:27], v[36:39]
	ds_read2_b64 v[44:47], v251 offset0:32 offset1:36
	s_waitcnt lgkmcnt(5)
	v_mfma_f32_16x16x32_bf16 v[36:39], v[226:229], v[28:31], v[36:39]
	ds_read2_b64 v[226:229], v251 offset0:40 offset1:44
	s_waitcnt lgkmcnt(5)
	v_mfma_f32_16x16x32_bf16 v[40:43], v[230:233], v[0:3], 0
	ds_read2_b64 v[230:233], v251 offset0:48 offset1:52
	s_waitcnt lgkmcnt(5)
	v_mfma_f32_16x16x32_bf16 v[40:43], v[238:241], v[4:7], v[40:43]
	ds_read2_b64 v[238:241], v251 offset0:56 offset1:60
	s_nop 1
	v_mul_f32_e32 v36, v34, v36
	v_mul_f32_e32 v37, v34, v37
	v_mul_f32_e32 v38, v34, v38
	v_mul_f32_e32 v39, v34, v39
	v_cvt_pk_bf16_f32 v48, v36, v37
	v_cvt_pk_bf16_f32 v49, v38, v39
	global_store_dwordx2 v[32:33], v[48:49], off offset:128
	s_waitcnt lgkmcnt(5)
	v_mfma_f32_16x16x32_bf16 v[40:43], v[242:245], v[8:11], v[40:43]
	v_add_u32_e32 v250, 0x10800, v35
	ds_read2_b64 v[242:245], v250 offset1:4
	s_waitcnt lgkmcnt(5)
	v_mfma_f32_16x16x32_bf16 v[40:43], v[246:249], v[12:15], v[40:43]
	ds_read2_b64 v[246:249], v250 offset0:8 offset1:12
	s_waitcnt lgkmcnt(5)
	v_mfma_f32_16x16x32_bf16 v[40:43], v[44:47], v[16:19], v[40:43]
	ds_read2_b64 v[44:47], v250 offset0:16 offset1:20
	s_waitcnt lgkmcnt(5)
	v_mfma_f32_16x16x32_bf16 v[40:43], v[226:229], v[20:23], v[40:43]
	ds_read2_b64 v[226:229], v250 offset0:24 offset1:28
	s_waitcnt lgkmcnt(5)
	v_mfma_f32_16x16x32_bf16 v[40:43], v[230:233], v[24:27], v[40:43]
	ds_read2_b64 v[230:233], v250 offset0:32 offset1:36
	s_waitcnt lgkmcnt(5)
	v_mfma_f32_16x16x32_bf16 v[40:43], v[238:241], v[28:31], v[40:43]
	ds_read2_b64 v[238:241], v250 offset0:40 offset1:44
	s_waitcnt lgkmcnt(5)
	v_mfma_f32_16x16x32_bf16 v[36:39], v[242:245], v[0:3], 0
	ds_read2_b64 v[242:245], v250 offset0:48 offset1:52
	s_waitcnt lgkmcnt(5)
; #define LAS __attribute__((address_space(3)))
; __device__ __forceinline__ unsigned cvt_pk_bf16(float lo, float hi) { unsigned r; asm volatile("v_cvt_pk_bf16_f32 %0, %1, %2" : "=v"(r) : "v"(lo), "v"(hi)); return r; }
; __global__ void __launch_bounds__(NTHREADS, 2) fwd_kernel(Params P) {
;     ...
;         for (int dt = 0; dt < 16; ++dt) {
;             f32x4 o = (f32x4){0.f, 0.f, 0.f, 0.f};
; #pragma unroll
;             for (int ks = 0; ks < 8; ++ks) {
;                 const LAS bf16_t* vp = KL + (dt * 16 + fr) * 264 + ks * 32 + 4 * fq;
;                 const u32x2 lo = *(const LAS u32x2*)vp, hi = *(const LAS u32x2*)(vp + 16);
;                 const u32x4 w = (u32x4){lo.x, lo.y, hi.x, hi.y};
;                 o = __builtin_amdgcn_mfma_f32_16x16x32_bf16(__builtin_bit_cast(bf16x8, w), pf[ks], o, 0, 0, 0);
;             }
;             u32x2 w; w.x = cvt_pk_bf16(o[0] * inv, o[1] * inv); w.y = cvt_pk_bf16(o[2] * inv, o[3] * inv);
;             *(u32x2*)(YS + (size_t)(row0 + fr) * 3072 + 2048 + h * HD + dt * 16 + 4 * fq) = w;
;         }
	v_mfma_f32_16x16x32_bf16 v[36:39], v[246:249], v[4:7], v[36:39]
	ds_read2_b64 v[246:249], v250 offset0:56 offset1:60
	s_nop 1
	v_mul_f32_e32 v40, v34, v40
	v_mul_f32_e32 v41, v34, v41
	v_mul_f32_e32 v42, v34, v42
	v_mul_f32_e32 v43, v34, v43
	v_cvt_pk_bf16_f32 v252, v40, v41
	v_cvt_pk_bf16_f32 v253, v42, v43
	global_store_dwordx2 v[32:33], v[252:253], off offset:160
	s_waitcnt lgkmcnt(5)
	v_mfma_f32_16x16x32_bf16 v[36:39], v[44:47], v[8:11], v[36:39]
	v_add_u32_e32 v251, 0x12900, v35
	ds_read2_b64 v[44:47], v251 offset1:4
	s_waitcnt lgkmcnt(5)
	v_mfma_f32_16x16x32_bf16 v[36:39], v[226:229], v[12:15], v[36:39]
	ds_read2_b64 v[226:229], v251 offset0:8 offset1:12
	s_waitcnt lgkmcnt(5)
	v_mfma_f32_16x16x32_bf16 v[36:39], v[230:233], v[16:19], v[36:39]
	ds_read2_b64 v[230:233], v251 offset0:16 offset1:20
	s_waitcnt lgkmcnt(5)
	v_mfma_f32_16x16x32_bf16 v[36:39], v[238:241], v[20:23], v[36:39]
	ds_read2_b64 v[238:241], v251 offset0:24 offset1:28
	s_waitcnt lgkmcnt(5)
	v_mfma_f32_16x16x32_bf16 v[36:39], v[242:245], v[24:27], v[36:39]
	ds_read2_b64 v[242:245], v251 offset0:32 offset1:36
	s_waitcnt lgkmcnt(5)
	v_mfma_f32_16x16x32_bf16 v[36:39], v[246:249], v[28:31], v[36:39]
	ds_read2_b64 v[246:249], v251 offset0:40 offset1:44
	s_waitcnt lgkmcnt(5)
	v_mfma_f32_16x16x32_bf16 v[40:43], v[44:47], v[0:3], 0
	ds_read2_b64 v[44:47], v251 offset0:48 offset1:52
	s_waitcnt lgkmcnt(5)
	v_mfma_f32_16x16x32_bf16 v[40:43], v[226:229], v[4:7], v[40:43]
	ds_read2_b64 v[226:229], v251 offset0:56 offset1:60
	s_nop 1
	v_mul_f32_e32 v36, v34, v36
	v_mul_f32_e32 v37, v34, v37
	v_mul_f32_e32 v38, v34, v38
	v_mul_f32_e32 v39, v34, v39
	v_cvt_pk_bf16_f32 v48, v36, v37
	v_cvt_pk_bf16_f32 v49, v38, v39
	global_store_dwordx2 v[32:33], v[48:49], off offset:192
	s_waitcnt lgkmcnt(5)
	v_mfma_f32_16x16x32_bf16 v[40:43], v[230:233], v[8:11], v[40:43]
	v_add_u32_e32 v250, 0x14a00, v35
	ds_read2_b64 v[230:233], v250 offset1:4
	s_waitcnt lgkmcnt(5)
	v_mfma_f32_16x16x32_bf16 v[40:43], v[238:241], v[12:15], v[40:43]
	ds_read2_b64 v[238:241], v250 offset0:8 offset1:12
	s_waitcnt lgkmcnt(5)
	v_mfma_f32_16x16x32_bf16 v[40:43], v[242:245], v[16:19], v[40:43]
	ds_read2_b64 v[242:245], v250 offset0:16 offset1:20
	s_waitcnt lgkmcnt(5)
	v_mfma_f32_16x16x32_bf16 v[40:43], v[246:249], v[20:23], v[40:43]
	ds_read2_b64 v[246:249], v250 offset0:24 offset1:28
	s_waitcnt lgkmcnt(5)
	v_mfma_f32_16x16x32_bf16 v[40:43], v[44:47], v[24:27], v[40:43]
	ds_read2_b64 v[44:47], v250 offset0:32 offset1:36
	s_waitcnt lgkmcnt(5)
	v_mfma_f32_16x16x32_bf16 v[40:43], v[226:229], v[28:31], v[40:43]
	ds_read2_b64 v[226:229], v250 offset0:40 offset1:44
	s_waitcnt lgkmcnt(5)
	v_mfma_f32_16x16x32_bf16 v[36:39], v[230:233], v[0:3], 0
	ds_read2_b64 v[230:233], v250 offset0:48 offset1:52
	s_waitcnt lgkmcnt(5)
	v_mfma_f32_16x16x32_bf16 v[36:39], v[238:241], v[4:7], v[36:39]
	ds_read2_b64 v[238:241], v250 offset0:56 offset1:60
	s_nop 1
	v_mul_f32_e32 v40, v34, v40
	v_mul_f32_e32 v41, v34, v41
	v_mul_f32_e32 v42, v34, v42
	v_mul_f32_e32 v43, v34, v43
	v_cvt_pk_bf16_f32 v252, v40, v41
	v_cvt_pk_bf16_f32 v253, v42, v43
	global_store_dwordx2 v[32:33], v[252:253], off offset:224
	s_waitcnt lgkmcnt(5)
	v_mfma_f32_16x16x32_bf16 v[36:39], v[242:245], v[8:11], v[36:39]
	v_add_u32_e32 v251, 0x16b00, v35
	ds_read2_b64 v[242:245], v251 offset1:4
	s_waitcnt lgkmcnt(5)
	v_mfma_f32_16x16x32_bf16 v[36:39], v[246:249], v[12:15], v[36:39]
	ds_read2_b64 v[246:249], v251 offset0:8 offset1:12
	s_waitcnt lgkmcnt(5)
	v_mfma_f32_16x16x32_bf16 v[36:39], v[44:47], v[16:19], v[36:39]
	ds_read2_b64 v[44:47], v251 offset0:16 offset1:20
	s_waitcnt lgkmcnt(5)
	v_mfma_f32_16x16x32_bf16 v[36:39], v[226:229], v[20:23], v[36:39]
	ds_read2_b64 v[226:229], v251 offset0:24 offset1:28
	s_waitcnt lgkmcnt(5)
	v_mfma_f32_16x16x32_bf16 v[36:39], v[230:233], v[24:27], v[36:39]
	ds_read2_b64 v[230:233], v251 offset0:32 offset1:36
	s_waitcnt lgkmcnt(5)
	v_mfma_f32_16x16x32_bf16 v[36:39], v[238:241], v[28:31], v[36:39]
	ds_read2_b64 v[238:241], v251 offset0:40 offset1:44
	s_waitcnt lgkmcnt(5)
	v_mfma_f32_16x16x32_bf16 v[40:43], v[242:245], v[0:3], 0
	ds_read2_b64 v[242:245], v251 offset0:48 offset1:52
	s_waitcnt lgkmcnt(5)
	v_mfma_f32_16x16x32_bf16 v[40:43], v[246:249], v[4:7], v[40:43]
	ds_read2_b64 v[246:249], v251 offset0:56 offset1:60
	s_nop 1
	v_mul_f32_e32 v36, v34, v36
	v_mul_f32_e32 v37, v34, v37
	v_mul_f32_e32 v38, v34, v38
	v_mul_f32_e32 v39, v34, v39
	v_cvt_pk_bf16_f32 v48, v36, v37
	v_cvt_pk_bf16_f32 v49, v38, v39
	global_store_dwordx2 v[32:33], v[48:49], off offset:256
	s_waitcnt lgkmcnt(5)
	v_mfma_f32_16x16x32_bf16 v[40:43], v[44:47], v[8:11], v[40:43]
	v_add_u32_e32 v250, 0x18c00, v35
	ds_read2_b64 v[44:47], v250 offset1:4
	s_waitcnt lgkmcnt(5)
	v_mfma_f32_16x16x32_bf16 v[40:43], v[226:229], v[12:15], v[40:43]
	ds_read2_b64 v[226:229], v250 offset0:8 offset1:12
	s_waitcnt lgkmcnt(5)
	v_mfma_f32_16x16x32_bf16 v[40:43], v[230:233], v[16:19], v[40:43]
	ds_read2_b64 v[230:233], v250 offset0:16 offset1:20
	s_waitcnt lgkmcnt(5)
	v_mfma_f32_16x16x32_bf16 v[40:43], v[238:241], v[20:23], v[40:43]
	ds_read2_b64 v[238:241], v250 offset0:24 offset1:28
	s_waitcnt lgkmcnt(5)
	v_mfma_f32_16x16x32_bf16 v[40:43], v[242:245], v[24:27], v[40:43]
	ds_read2_b64 v[242:245], v250 offset0:32 offset1:36
	s_waitcnt lgkmcnt(5)
	v_mfma_f32_16x16x32_bf16 v[40:43], v[246:249], v[28:31], v[40:43]
	ds_read2_b64 v[246:249], v250 offset0:40 offset1:44
	s_waitcnt lgkmcnt(5)
	v_mfma_f32_16x16x32_bf16 v[36:39], v[44:47], v[0:3], 0
	ds_read2_b64 v[44:47], v250 offset0:48 offset1:52
	s_waitcnt lgkmcnt(5)
; #define LAS __attribute__((address_space(3)))
; __device__ __forceinline__ unsigned cvt_pk_bf16(float lo, float hi) { unsigned r; asm volatile("v_cvt_pk_bf16_f32 %0, %1, %2" : "=v"(r) : "v"(lo), "v"(hi)); return r; }
; __global__ void __launch_bounds__(NTHREADS, 2) fwd_kernel(Params P) {
;     ...
;         for (int dt = 0; dt < 16; ++dt) {
;             f32x4 o = (f32x4){0.f, 0.f, 0.f, 0.f};
; #pragma unroll
;             for (int ks = 0; ks < 8; ++ks) {
;                 const LAS bf16_t* vp = KL + (dt * 16 + fr) * 264 + ks * 32 + 4 * fq;
;                 const u32x2 lo = *(const LAS u32x2*)vp, hi = *(const LAS u32x2*)(vp + 16);
;                 const u32x4 w = (u32x4){lo.x, lo.y, hi.x, hi.y};
;                 o = __builtin_amdgcn_mfma_f32_16x16x32_bf16(__builtin_bit_cast(bf16x8, w), pf[ks], o, 0, 0, 0);
;             }
;             u32x2 w; w.x = cvt_pk_bf16(o[0] * inv, o[1] * inv); w.y = cvt_pk_bf16(o[2] * inv, o[3] * inv);
;             *(u32x2*)(YS + (size_t)(row0 + fr) * 3072 + 2048 + h * HD + dt * 16 + 4 * fq) = w;
;         }
;     }
;     if (!dfirst_ && PHON(8)) p5d_sample_attn(P, lds, bid, G, tid);
	v_mfma_f32_16x16x32_bf16 v[36:39], v[226:229], v[4:7], v[36:39]
	ds_read2_b64 v[226:229], v250 offset0:56 offset1:60
	s_nop 1
	v_mul_f32_e32 v40, v34, v40
	v_mul_f32_e32 v41, v34, v41
	v_mul_f32_e32 v42, v34, v42
	v_mul_f32_e32 v43, v34, v43
	v_cvt_pk_bf16_f32 v252, v40, v41
	v_cvt_pk_bf16_f32 v253, v42, v43
	global_store_dwordx2 v[32:33], v[252:253], off offset:288
	s_waitcnt lgkmcnt(5)
	v_mfma_f32_16x16x32_bf16 v[36:39], v[230:233], v[8:11], v[36:39]
	v_add_u32_e32 v251, 0x1ad00, v35
	ds_read2_b64 v[230:233], v251 offset1:4
	s_waitcnt lgkmcnt(5)
	v_mfma_f32_16x16x32_bf16 v[36:39], v[238:241], v[12:15], v[36:39]
	ds_read2_b64 v[238:241], v251 offset0:8 offset1:12
	s_waitcnt lgkmcnt(5)
	v_mfma_f32_16x16x32_bf16 v[36:39], v[242:245], v[16:19], v[36:39]
	ds_read2_b64 v[242:245], v251 offset0:16 offset1:20
	s_waitcnt lgkmcnt(5)
	v_mfma_f32_16x16x32_bf16 v[36:39], v[246:249], v[20:23], v[36:39]
	ds_read2_b64 v[246:249], v251 offset0:24 offset1:28
	s_waitcnt lgkmcnt(5)
	v_mfma_f32_16x16x32_bf16 v[36:39], v[44:47], v[24:27], v[36:39]
	ds_read2_b64 v[44:47], v251 offset0:32 offset1:36
	s_waitcnt lgkmcnt(5)
	v_mfma_f32_16x16x32_bf16 v[36:39], v[226:229], v[28:31], v[36:39]
	ds_read2_b64 v[226:229], v251 offset0:40 offset1:44
	s_waitcnt lgkmcnt(5)
	v_mfma_f32_16x16x32_bf16 v[40:43], v[230:233], v[0:3], 0
	ds_read2_b64 v[230:233], v251 offset0:48 offset1:52
	s_waitcnt lgkmcnt(5)
	v_mfma_f32_16x16x32_bf16 v[40:43], v[238:241], v[4:7], v[40:43]
	ds_read2_b64 v[238:241], v251 offset0:56 offset1:60
	s_nop 1
	v_mul_f32_e32 v36, v34, v36
	v_mul_f32_e32 v37, v34, v37
	v_mul_f32_e32 v38, v34, v38
	v_mul_f32_e32 v39, v34, v39
	v_cvt_pk_bf16_f32 v48, v36, v37
	v_cvt_pk_bf16_f32 v49, v38, v39
	global_store_dwordx2 v[32:33], v[48:49], off offset:320
	s_waitcnt lgkmcnt(5)
	v_mfma_f32_16x16x32_bf16 v[40:43], v[242:245], v[8:11], v[40:43]
	v_add_u32_e32 v250, 0x1ce00, v35
	ds_read2_b64 v[242:245], v250 offset1:4
	s_waitcnt lgkmcnt(5)
	v_mfma_f32_16x16x32_bf16 v[40:43], v[246:249], v[12:15], v[40:43]
	ds_read2_b64 v[246:249], v250 offset0:8 offset1:12
	s_waitcnt lgkmcnt(5)
	v_mfma_f32_16x16x32_bf16 v[40:43], v[44:47], v[16:19], v[40:43]
	ds_read2_b64 v[44:47], v250 offset0:16 offset1:20
	s_waitcnt lgkmcnt(5)
	v_mfma_f32_16x16x32_bf16 v[40:43], v[226:229], v[20:23], v[40:43]
	ds_read2_b64 v[226:229], v250 offset0:24 offset1:28
	s_waitcnt lgkmcnt(5)
	v_mfma_f32_16x16x32_bf16 v[40:43], v[230:233], v[24:27], v[40:43]
	ds_read2_b64 v[230:233], v250 offset0:32 offset1:36
	s_waitcnt lgkmcnt(5)
	v_mfma_f32_16x16x32_bf16 v[40:43], v[238:241], v[28:31], v[40:43]
	ds_read2_b64 v[238:241], v250 offset0:40 offset1:44
	s_waitcnt lgkmcnt(5)
	v_mfma_f32_16x16x32_bf16 v[36:39], v[242:245], v[0:3], 0
	ds_read2_b64 v[242:245], v250 offset0:48 offset1:52
	s_waitcnt lgkmcnt(5)
	v_mfma_f32_16x16x32_bf16 v[36:39], v[246:249], v[4:7], v[36:39]
	ds_read2_b64 v[246:249], v250 offset0:56 offset1:60
	s_nop 1
	v_mul_f32_e32 v40, v34, v40
	v_mul_f32_e32 v41, v34, v41
	v_mul_f32_e32 v42, v34, v42
	v_mul_f32_e32 v43, v34, v43
	v_cvt_pk_bf16_f32 v252, v40, v41
	v_cvt_pk_bf16_f32 v253, v42, v43
	global_store_dwordx2 v[32:33], v[252:253], off offset:352
	s_waitcnt lgkmcnt(5)
	v_mfma_f32_16x16x32_bf16 v[36:39], v[44:47], v[8:11], v[36:39]
	v_add_u32_e32 v251, 0x1ef00, v35
	ds_read2_b64 v[44:47], v251 offset1:4
	s_waitcnt lgkmcnt(5)
	v_mfma_f32_16x16x32_bf16 v[36:39], v[226:229], v[12:15], v[36:39]
	ds_read2_b64 v[226:229], v251 offset0:8 offset1:12
	s_waitcnt lgkmcnt(5)
	v_mfma_f32_16x16x32_bf16 v[36:39], v[230:233], v[16:19], v[36:39]
	ds_read2_b64 v[230:233], v251 offset0:16 offset1:20
	s_waitcnt lgkmcnt(5)
	v_mfma_f32_16x16x32_bf16 v[36:39], v[238:241], v[20:23], v[36:39]
	ds_read2_b64 v[238:241], v251 offset0:24 offset1:28
	s_waitcnt lgkmcnt(5)
	v_mfma_f32_16x16x32_bf16 v[36:39], v[242:245], v[24:27], v[36:39]
	ds_read2_b64 v[242:245], v251 offset0:32 offset1:36
	s_waitcnt lgkmcnt(5)
	v_mfma_f32_16x16x32_bf16 v[36:39], v[246:249], v[28:31], v[36:39]
	ds_read2_b64 v[246:249], v251 offset0:40 offset1:44
	s_waitcnt lgkmcnt(5)
	v_mfma_f32_16x16x32_bf16 v[40:43], v[44:47], v[0:3], 0
	ds_read2_b64 v[44:47], v251 offset0:48 offset1:52
	s_waitcnt lgkmcnt(5)
	v_mfma_f32_16x16x32_bf16 v[40:43], v[226:229], v[4:7], v[40:43]
	ds_read2_b64 v[226:229], v251 offset0:56 offset1:60
	s_nop 1
	v_mul_f32_e32 v36, v34, v36
	v_mul_f32_e32 v37, v34, v37
	v_mul_f32_e32 v38, v34, v38
	v_mul_f32_e32 v39, v34, v39
	v_cvt_pk_bf16_f32 v48, v36, v37
	v_cvt_pk_bf16_f32 v49, v38, v39
	global_store_dwordx2 v[32:33], v[48:49], off offset:384
	s_waitcnt lgkmcnt(5)
	v_mfma_f32_16x16x32_bf16 v[40:43], v[230:233], v[8:11], v[40:43]
	s_waitcnt lgkmcnt(4)
	v_mfma_f32_16x16x32_bf16 v[40:43], v[238:241], v[12:15], v[40:43]
	s_waitcnt lgkmcnt(3)
	v_mfma_f32_16x16x32_bf16 v[40:43], v[242:245], v[16:19], v[40:43]
	s_waitcnt lgkmcnt(2)
	v_mfma_f32_16x16x32_bf16 v[40:43], v[246:249], v[20:23], v[40:43]
	s_waitcnt lgkmcnt(1)
	v_mfma_f32_16x16x32_bf16 v[40:43], v[44:47], v[24:27], v[40:43]
	s_waitcnt lgkmcnt(0)
	v_mfma_f32_16x16x32_bf16 v[40:43], v[226:229], v[28:31], v[40:43]
	s_nop 7
	s_nop 1
	v_mul_f32_e32 v40, v34, v40
	v_mul_f32_e32 v41, v34, v41
	v_mul_f32_e32 v42, v34, v42
	v_mul_f32_e32 v43, v34, v43
	v_cvt_pk_bf16_f32 v252, v40, v41
	v_cvt_pk_bf16_f32 v253, v42, v43
	global_store_dwordx2 v[32:33], v[252:253], off offset:416
	s_add_i32 s17, s17, s94
	s_add_i32 s3, s3, s10
	s_add_i32 s11, s11, s12
	s_cmpk_gt_i32 s17, 0xff
	s_cbranch_scc0 .LBB0_628
.LBB0_631:
	s_waitcnt lgkmcnt(0)
	s_barrier
	s_and_b64 vcc, exec, s[60:61]
	s_cbranch_vccz .LBB0_641
	v_mov_b32_e32 v128, v178
	s_and_b32 s1, s94, 7
	s_cmp_lg_u32 s1, 0
	v_readfirstlane_b32 s0, v128
	s_mov_b32 s2, s34
	s_cbranch_scc0 .LBB0_634
	s_cmpk_gt_i32 s2, 0x1ff
	s_cbranch_scc0 .LBB0_635
	s_branch .LBB0_641

; __device__ __forceinline__ void ln_row(const float* yrow, const float* g, const float* b, float* of, bf16_t* ob, int lane) {
;     f32x4 v[8]; float s = 0.f;
; #pragma unroll
;     for (int j = 0; j < 8; ++j) { v[j] = *(const f32x4*)(yrow + 4 * lane + 256 * j); s += (v[j][0] + v[j][1]) + (v[j][2] + v[j][3]); }
;     const float mean = wave_sum(s) * (1.f / D); float s2 = 0.f;
; #pragma unroll
;     for (int j = 0; j < 8; ++j) { v[j] = v[j] - mean; s2 += (v[j][0] * v[j][0] + v[j][1] * v[j][1]) + (v[j][2] * v[j][2] + v[j][3] * v[j][3]); }
;     const float rstd = 1.0f / sqrtf(wave_sum(s2) * (1.f / D) + LN_EPS);
; #pragma unroll
;     for (int j = 0; j < 8; ++j) {
;         const f32x4 gg = *(const f32x4*)(g + 4 * lane + 256 * j), bb = *(const f32x4*)(b + 4 * lane + 256 * j);
; __global__ void __launch_bounds__(NTHREADS, 2) fwd_kernel(Params P) {
;     ...
;     if (PHON(16)) for (int r = gw; r < MR; r += NGW) ln_row(Y + (size_t)r * D, P.in[I_LN3G], P.in[I_LN3B], out + O_Y + (size_t)r * D, nullptr, lane);
.LBB0_1179:
	s_or_b64 exec, exec, s[0:1]
	v_readlane_b32 s0, v255, 31
	v_readlane_b32 s1, v255, 32
	s_andn2_b64 vcc, exec, s[0:1]
	s_waitcnt lgkmcnt(0)
	s_barrier
	s_cbranch_vccnz .LBB0_1184
	v_mbcnt_hi_u32_b32 v0, -1, v179
	v_and_b32_e32 v1, 64, v0
	v_add_u32_e32 v1, 64, v1
	v_xor_b32_e32 v2, 1, v0
	v_cmp_lt_i32_e32 vcc, v2, v1
	v_readlane_b32 s0, v254, 0
	v_readlane_b32 s6, v254, 6
	v_cndmask_b32_e32 v2, v0, v2, vcc
	v_lshlrev_b32_e32 v52, 2, v2
	v_xor_b32_e32 v2, 2, v0
	v_cmp_lt_i32_e32 vcc, v2, v1
	v_readlane_b32 s7, v254, 7
	v_readlane_b32 s2, v254, 2
	v_cndmask_b32_e32 v2, v0, v2, vcc
	v_lshlrev_b32_e32 v53, 2, v2
	v_xor_b32_e32 v2, 4, v0
	v_cmp_lt_i32_e32 vcc, v2, v1
	v_readlane_b32 s3, v254, 3
	v_readlane_b32 s4, v254, 4
	v_cndmask_b32_e32 v2, v0, v2, vcc
	v_readlane_b32 s5, v254, 5
	s_mov_b64 s[10:11], s[6:7]
	v_lshlrev_b32_e32 v54, 2, v2
	v_xor_b32_e32 v2, 8, v0
	v_mov_b32_e32 v177, 0
	s_mov_b64 s[8:9], s[4:5]
	s_mov_b64 s[6:7], s[2:3]
	v_cmp_lt_i32_e32 vcc, v2, v1
	v_lshl_add_u64 v[32:33], s[6:7], 0, v[176:177]
	v_lshl_add_u64 v[34:35], s[8:9], 0, v[176:177]
	s_mov_b64 s[2:3], 0x1000
	v_cndmask_b32_e32 v2, v0, v2, vcc
	v_lshl_add_u64 v[36:37], v[32:33], 0, s[2:3]
	v_lshl_add_u64 v[38:39], v[34:35], 0, s[2:3]
	s_mov_b64 s[2:3], 0x1400
	v_lshlrev_b32_e32 v55, 2, v2
	v_xor_b32_e32 v2, 16, v0
	v_lshl_add_u64 v[40:41], v[32:33], 0, s[2:3]
	v_lshl_add_u64 v[42:43], v[34:35], 0, s[2:3]
	s_mov_b64 s[2:3], 0x1800
	v_cmp_lt_i32_e32 vcc, v2, v1
	v_readlane_b32 s1, v254, 1
	s_cmp_lg_u64 s[10:11], 0
	v_lshl_add_u64 v[44:45], v[32:33], 0, s[2:3]
	v_lshl_add_u64 v[46:47], v[34:35], 0, s[2:3]
	s_mov_b64 s[2:3], 0x1c00
	v_cndmask_b32_e32 v2, v0, v2, vcc
	s_cselect_b64 s[0:1], -1, 0
	v_lshl_add_u64 v[48:49], v[32:33], 0, s[2:3]
	v_lshl_add_u64 v[50:51], v[34:35], 0, s[2:3]
	s_lshl_b64 s[2:3], s[68:69], 13
	v_lshlrev_b32_e32 v56, 2, v2
	v_xor_b32_e32 v2, 32, v0
	s_add_u32 s4, s92, s2
	v_cmp_lt_i32_e32 vcc, v2, v1
	s_addc_u32 s5, s93, s3
	s_ashr_i32 s71, s70, 31
	v_cndmask_b32_e32 v0, v0, v2, vcc
	s_lshl_b64 s[6:7], s[70:71], 13
	v_lshlrev_b32_e32 v57, 2, v0
	s_add_u32 s8, s10, s2
	v_cndmask_b32_e64 v0, 0, 1, s[0:1]
	s_addc_u32 s9, s11, s3
	s_mov_b32 s10, 0x1a321000
	v_cmp_ne_u32_e64 s[0:1], 1, v0
	v_mov_b32_e32 v58, 0x3727c5ac
	s_mov_b32 s11, 0xf800000
	v_mov_b32_e32 v59, 0x260
	s_movk_i32 s12, 0x1000
	global_load_dwordx4 v[100:103], v[32:33], off
	global_load_dwordx4 v[104:107], v[34:35], off
	global_load_dwordx4 v[108:111], v[32:33], off offset:1024
	global_load_dwordx4 v[112:115], v[34:35], off offset:1024
	global_load_dwordx4 v[116:119], v[32:33], off offset:2048
	global_load_dwordx4 v[120:123], v[34:35], off offset:2048
	global_load_dwordx4 v[124:127], v[32:33], off offset:3072
	global_load_dwordx4 v[128:131], v[34:35], off offset:3072
	global_load_dwordx4 v[132:135], v[36:37], off
	global_load_dwordx4 v[136:139], v[38:39], off
	global_load_dwordx4 v[140:143], v[40:41], off
	global_load_dwordx4 v[144:147], v[42:43], off
	global_load_dwordx4 v[148:151], v[44:45], off
	global_load_dwordx4 v[152:155], v[46:47], off
	global_load_dwordx4 v[156:159], v[48:49], off
	global_load_dwordx4 v[160:163], v[50:51], off
	s_waitcnt vmcnt(0)
	s_branch .LBB0_1182

; __device__ __forceinline__ void ln_row(const float* yrow, const float* g, const float* b, float* of, bf16_t* ob, int lane) {
;     f32x4 v[8]; float s = 0.f;
; #pragma unroll
;     for (int j = 0; j < 8; ++j) { v[j] = *(const f32x4*)(yrow + 4 * lane + 256 * j); s += (v[j][0] + v[j][1]) + (v[j][2] + v[j][3]); }
;     const float mean = wave_sum(s) * (1.f / D); float s2 = 0.f;
; #pragma unroll
;     for (int j = 0; j < 8; ++j) { v[j] = v[j] - mean; s2 += (v[j][0] * v[j][0] + v[j][1] * v[j][1]) + (v[j][2] * v[j][2] + v[j][3] * v[j][3]); }
;     const float rstd = 1.0f / sqrtf(wave_sum(s2) * (1.f / D) + LN_EPS);
.LBB0_1182:
	v_lshl_add_u64 v[16:17], s[4:5], 0, v[176:177]
	v_add_co_u32_e32 v18, vcc, s10, v16
	s_nop 1
	v_addc_co_u32_e32 v19, vcc, 0, v17, vcc
	v_add_co_u32_e32 v60, vcc, 0x1a320000, v16
	global_load_dwordx4 v[8:11], v[18:19], off
	global_load_dwordx4 v[12:15], v[18:19], off offset:1024
	global_load_dwordx4 v[4:7], v[18:19], off offset:2048
	global_load_dwordx4 v[0:3], v[18:19], off offset:3072
	s_waitcnt lgkmcnt(0)
	v_addc_co_u32_e32 v61, vcc, 0, v17, vcc
	global_load_dwordx4 v[28:31], v[60:61], off
	global_load_dwordx4 v[24:27], v[60:61], off offset:1024
	global_load_dwordx4 v[20:23], v[60:61], off offset:2048
	global_load_dwordx4 v[16:19], v[60:61], off offset:3072
	s_and_b64 vcc, exec, s[0:1]
	s_waitcnt vmcnt(7)
	v_mov_b32_e32 v63, v10
	s_waitcnt vmcnt(6)
	v_mov_b32_e32 v66, v13
	v_mov_b32_e32 v67, v14
	v_mov_b32_e32 v68, v12
	v_mov_b32_e32 v69, v15
	s_waitcnt vmcnt(5)
	v_add_f32_e32 v70, v4, v5
	v_add_f32_e32 v72, v6, v7
	s_waitcnt vmcnt(4)
	v_mov_b32_e32 v71, v2
	v_mov_b32_e32 v73, v3
	s_waitcnt vmcnt(3)
	v_mov_b32_e32 v74, v28
	s_waitcnt vmcnt(2)
	v_mov_b32_e32 v75, v24
	v_mov_b32_e32 v76, v29
	v_mov_b32_e32 v77, v25
	v_mov_b32_e32 v78, v30
	v_mov_b32_e32 v79, v26
	v_mov_b32_e32 v80, v31
	v_mov_b32_e32 v81, v27
	v_mov_b32_e32 v65, v11
	s_waitcnt vmcnt(1)
	v_mov_b32_e32 v82, v21
	v_mov_b32_e32 v83, v22
	v_mov_b32_e32 v84, v20
	v_mov_b32_e32 v85, v23
	s_waitcnt vmcnt(0)
	v_add_f32_e32 v62, v16, v17
	v_add_f32_e32 v64, v18, v19
	v_pk_add_f32 v[66:67], v[66:67], v[68:69]
	v_pk_add_f32 v[68:69], v[70:71], v[72:73]
	v_pk_add_f32 v[70:71], v[74:75], v[76:77]
	v_pk_add_f32 v[72:73], v[78:79], v[80:81]
	v_pk_add_f32 v[74:75], v[82:83], v[84:85]
	v_pk_add_f32 v[62:63], v[62:63], v[64:65]
	v_pk_add_f32 v[64:65], v[66:67], v[66:67] op_sel:[0,1] op_sel_hi:[1,0]
	v_pk_add_f32 v[66:67], v[70:71], v[72:73]
	v_pk_add_f32 v[70:71], v[74:75], v[74:75] op_sel:[0,1] op_sel_hi:[1,0]
	v_add_f32_e32 v60, 0, v66
	v_mov_b32_e32 v61, v8
	v_mov_b32_e32 v71, v9
	v_add_f32_e32 v60, v60, v67
	v_pk_add_f32 v[60:61], v[60:61], v[70:71]
	v_mov_b32_e32 v65, v1
	v_pk_add_f32 v[60:61], v[60:61], v[62:63]
	s_nop 0
	v_pk_add_f32 v[60:61], v[60:61], v[60:61] op_sel:[0,1] op_sel_hi:[1,0]
	s_nop 0
	v_mov_b32_e32 v61, v0
	v_pk_add_f32 v[60:61], v[60:61], v[64:65]
	s_nop 0
	v_pk_add_f32 v[60:61], v[60:61], v[68:69]
	s_nop 0
	v_add_f32_e32 v60, v60, v61
	ds_bpermute_b32 v61, v52, v60
	s_waitcnt lgkmcnt(0)
	v_add_f32_e32 v60, v60, v61
	ds_bpermute_b32 v61, v53, v60
	s_waitcnt lgkmcnt(0)
	v_add_f32_e32 v60, v60, v61
	ds_bpermute_b32 v61, v54, v60
	s_waitcnt lgkmcnt(0)
	v_add_f32_e32 v60, v60, v61
	ds_bpermute_b32 v61, v55, v60
	s_waitcnt lgkmcnt(0)
	v_add_f32_e32 v60, v60, v61
	ds_bpermute_b32 v61, v56, v60
	s_waitcnt lgkmcnt(0)
	v_add_f32_e32 v60, v60, v61
	ds_bpermute_b32 v61, v57, v60
	s_waitcnt lgkmcnt(0)
	v_add_f32_e32 v60, v60, v61
	v_fmamk_f32 v31, v60, 0xba000000, v31
	v_fmamk_f32 v29, v60, 0xba000000, v29
	v_fmamk_f32 v27, v60, 0xba000000, v27
	v_fmamk_f32 v25, v60, 0xba000000, v25
	v_fmamk_f32 v30, v60, 0xba000000, v30
	v_fmac_f32_e32 v28, 0xba000000, v60
	v_fmamk_f32 v26, v60, 0xba000000, v26
	v_fmac_f32_e32 v24, 0xba000000, v60
	v_fmamk_f32 v23, v60, 0xba000000, v23
	v_fmamk_f32 v21, v60, 0xba000000, v21
	v_mul_f32_e32 v61, v29, v29
	v_mul_f32_e32 v62, v31, v31
	v_mul_f32_e32 v63, v25, v25
	v_mul_f32_e32 v64, v27, v27
	v_fmamk_f32 v22, v60, 0xba000000, v22
	v_fmac_f32_e32 v20, 0xba000000, v60
	v_fmamk_f32 v19, v60, 0xba000000, v19
	v_fmamk_f32 v17, v60, 0xba000000, v17
	v_mul_f32_e32 v65, v21, v21
	v_mul_f32_e32 v66, v23, v23
	v_fmac_f32_e32 v61, v28, v28
	v_fmac_f32_e32 v62, v30, v30
	v_fmac_f32_e32 v63, v24, v24
	v_fmac_f32_e32 v64, v26, v26
	v_fmamk_f32 v18, v60, 0xba000000, v18
	v_fmac_f32_e32 v16, 0xba000000, v60
	v_fmamk_f32 v11, v60, 0xba000000, v11
	v_fmamk_f32 v9, v60, 0xba000000, v9
	v_mul_f32_e32 v67, v17, v17
	v_mul_f32_e32 v68, v19, v19
	v_fmac_f32_e32 v65, v20, v20
	v_fmac_f32_e32 v66, v22, v22
	v_add_f32_e32 v61, v61, v62
	v_add_f32_e32 v62, v63, v64
	v_fmamk_f32 v10, v60, 0xba000000, v10
	v_fmac_f32_e32 v8, 0xba000000, v60
	v_fmamk_f32 v15, v60, 0xba000000, v15
	v_fmamk_f32 v13, v60, 0xba000000, v13
	v_mul_f32_e32 v69, v9, v9
	v_mul_f32_e32 v70, v11, v11
	v_fmac_f32_e32 v67, v16, v16
	v_fmac_f32_e32 v68, v18, v18
	v_add_f32_e32 v63, v65, v66
	v_add_f32_e32 v61, v61, v62
	v_fmamk_f32 v14, v60, 0xba000000, v14
	v_fmac_f32_e32 v12, 0xba000000, v60
	v_fmamk_f32 v7, v60, 0xba000000, v7
	v_fmamk_f32 v5, v60, 0xba000000, v5
	v_mul_f32_e32 v71, v13, v13
	v_mul_f32_e32 v72, v15, v15
	v_fmac_f32_e32 v69, v8, v8
	v_fmac_f32_e32 v70, v10, v10
	v_add_f32_e32 v64, v67, v68
	v_add_f32_e32 v61, v63, v61
	v_fmamk_f32 v6, v60, 0xba000000, v6
	v_fmac_f32_e32 v4, 0xba000000, v60
	v_mul_f32_e32 v73, v5, v5
	v_fmac_f32_e32 v71, v12, v12
	v_fmac_f32_e32 v72, v14, v14
	v_add_f32_e32 v65, v69, v70
	v_add_f32_e32 v61, v64, v61
	v_mul_f32_e32 v62, v7, v7
	v_fmac_f32_e32 v73, v4, v4
	v_add_f32_e32 v66, v71, v72
	v_add_f32_e32 v61, v65, v61
	v_fmac_f32_e32 v62, v6, v6
	v_add_f32_e32 v61, v66, v61
	v_add_f32_e32 v62, v73, v62
	v_fmamk_f32 v3, v60, 0xba000000, v3
	v_fmamk_f32 v1, v60, 0xba000000, v1
	v_add_f32_e32 v61, v62, v61
	v_fmamk_f32 v2, v60, 0xba000000, v2
	v_fmac_f32_e32 v0, 0xba000000, v60
	v_mul_f32_e32 v60, v1, v1
	v_mul_f32_e32 v62, v3, v3
	v_fmac_f32_e32 v60, v0, v0
	v_fmac_f32_e32 v62, v2, v2
	v_add_f32_e32 v60, v60, v62
	v_add_f32_e32 v60, v60, v61
	ds_bpermute_b32 v61, v52, v60
	s_waitcnt lgkmcnt(0)
	v_add_f32_e32 v60, v60, v61
	ds_bpermute_b32 v61, v53, v60
	s_waitcnt lgkmcnt(0)
	v_add_f32_e32 v60, v60, v61
	ds_bpermute_b32 v61, v54, v60
	s_waitcnt lgkmcnt(0)
	v_add_f32_e32 v60, v60, v61
	ds_bpermute_b32 v61, v55, v60
	s_waitcnt lgkmcnt(0)
	v_add_f32_e32 v60, v60, v61
	ds_bpermute_b32 v61, v56, v60
	s_waitcnt lgkmcnt(0)
	v_add_f32_e32 v60, v60, v61
	ds_bpermute_b32 v61, v57, v60
	s_cbranch_vccnz .LBB0_1181
; __device__ __forceinline__ unsigned cvt_pk_bf16(float lo, float hi) { unsigned r; asm volatile("v_cvt_pk_bf16_f32 %0, %1, %2" : "=v"(r) : "v"(lo), "v"(hi)); return r; }
; __device__ __forceinline__ void ln_row(const float* yrow, const float* g, const float* b, float* of, bf16_t* ob, int lane) {
;     ...
;     const float rstd = 1.0f / sqrtf(wave_sum(s2) * (1.f / D) + LN_EPS);
; #pragma unroll
;     for (int j = 0; j < 8; ++j) {
;         const f32x4 gg = *(const f32x4*)(g + 4 * lane + 256 * j), bb = *(const f32x4*)(b + 4 * lane + 256 * j);
;         const f32x4 o = v[j] * rstd * gg + bb;
;         if (of) __builtin_nontemporal_store(o, (f32x4*)(of + 4 * lane + 256 * j));
;         if (ob) { u32x2 w; w.x = cvt_pk_bf16(o[0], o[1]); w.y = cvt_pk_bf16(o[2], o[3]); *(u32x2*)(ob + 4 * lane + 256 * j) = w; }
;     }
	v_mov_b32_e32 v62, v100
	v_mov_b32_e32 v63, v101
	v_mov_b32_e32 v64, v102
	v_mov_b32_e32 v65, v103
	v_mov_b32_e32 v66, v104
	v_mov_b32_e32 v67, v105
	v_mov_b32_e32 v68, v106
	v_mov_b32_e32 v69, v107
	s_waitcnt lgkmcnt(0)
	v_add_f32_e32 v60, v60, v61
	v_fmamk_f32 v60, v60, 0x3a000000, v58
	v_mul_f32_e32 v61, 0x4f800000, v60
	v_cmp_gt_f32_e32 vcc, s11, v60
	s_nop 1
	v_cndmask_b32_e32 v60, v60, v61, vcc
	v_sqrt_f32_e32 v61, v60
	s_nop 0
	v_add_u32_e32 v70, -1, v61
	v_add_u32_e32 v71, 1, v61
	v_fma_f32 v72, -v70, v61, v60
	v_fma_f32 v73, -v71, v61, v60
	v_cmp_ge_f32_e64 s[2:3], 0, v72
	s_nop 1
	v_cndmask_b32_e64 v61, v61, v70, s[2:3]
	v_cmp_lt_f32_e64 s[2:3], 0, v73
	s_nop 1
	v_cndmask_b32_e64 v61, v61, v71, s[2:3]
	v_mul_f32_e32 v70, 0x37800000, v61
	v_cndmask_b32_e32 v61, v61, v70, vcc
	v_cmp_class_f32_e32 vcc, v60, v59
	v_lshl_add_u64 v[70:71], s[8:9], 0, v[176:177]
	s_nop 0
	v_cndmask_b32_e32 v60, v61, v60, vcc
	v_div_scale_f32 v61, s[2:3], v60, v60, 1.0
	v_rcp_f32_e32 v72, v61
	v_div_scale_f32 v73, vcc, 1.0, v60, 1.0
	v_fma_f32 v74, -v61, v72, 1.0
	v_fmac_f32_e32 v72, v74, v72
	v_mul_f32_e32 v74, v73, v72
	v_fma_f32 v75, -v61, v74, v73
	v_fmac_f32_e32 v74, v75, v72
	v_fma_f32 v61, -v61, v74, v73
	v_div_fmas_f32 v61, v61, v72, v74
	v_div_fixup_f32 v72, v61, v60, 1.0
	v_pk_mul_f32 v[28:29], v[28:29], v[72:73] op_sel_hi:[1,0]
	v_pk_mul_f32 v[30:31], v[30:31], v[72:73] op_sel_hi:[1,0]
	v_pk_mul_f32 v[26:27], v[26:27], v[72:73] op_sel_hi:[1,0]
	v_pk_mul_f32 v[24:25], v[24:25], v[72:73] op_sel_hi:[1,0]
	v_pk_mul_f32 v[22:23], v[22:23], v[72:73] op_sel_hi:[1,0]
	v_pk_mul_f32 v[20:21], v[20:21], v[72:73] op_sel_hi:[1,0]
	v_pk_mul_f32 v[18:19], v[18:19], v[72:73] op_sel_hi:[1,0]
	v_pk_mul_f32 v[16:17], v[16:17], v[72:73] op_sel_hi:[1,0]
	v_pk_mul_f32 v[10:11], v[10:11], v[72:73] op_sel_hi:[1,0]
	v_pk_mul_f32 v[8:9], v[8:9], v[72:73] op_sel_hi:[1,0]
	v_pk_mul_f32 v[14:15], v[14:15], v[72:73] op_sel_hi:[1,0]
	v_pk_mul_f32 v[12:13], v[12:13], v[72:73] op_sel_hi:[1,0]
	v_pk_mul_f32 v[6:7], v[6:7], v[72:73] op_sel_hi:[1,0]
	v_pk_mul_f32 v[4:5], v[4:5], v[72:73] op_sel_hi:[1,0]
	v_pk_mul_f32 v[2:3], v[2:3], v[72:73] op_sel_hi:[1,0]
	v_pk_mul_f32 v[0:1], v[0:1], v[72:73] op_sel_hi:[1,0]
	v_pk_fma_f32 v[30:31], v[30:31], v[64:65], v[68:69]
	v_pk_fma_f32 v[28:29], v[28:29], v[62:63], v[66:67]
	global_store_dwordx4 v[70:71], v[28:31], off nt
	s_nop 1
	v_mov_b32_e32 v28, v108
	v_mov_b32_e32 v29, v109
	v_mov_b32_e32 v30, v110
	v_mov_b32_e32 v31, v111
	v_mov_b32_e32 v60, v112
	v_mov_b32_e32 v61, v113
	v_mov_b32_e32 v62, v114
	v_mov_b32_e32 v63, v115
	v_pk_fma_f32 v[24:25], v[24:25], v[28:29], v[60:61]
	v_pk_fma_f32 v[26:27], v[26:27], v[30:31], v[62:63]
	global_store_dwordx4 v[70:71], v[24:27], off offset:1024 nt
	s_nop 1
	v_mov_b32_e32 v24, v116
	v_mov_b32_e32 v25, v117
	v_mov_b32_e32 v26, v118
	v_mov_b32_e32 v27, v119
	v_mov_b32_e32 v28, v120
	v_mov_b32_e32 v29, v121
	v_mov_b32_e32 v30, v122
	v_mov_b32_e32 v31, v123
	v_pk_fma_f32 v[20:21], v[20:21], v[24:25], v[28:29]
	v_pk_fma_f32 v[22:23], v[22:23], v[26:27], v[30:31]
	global_store_dwordx4 v[70:71], v[20:23], off offset:2048 nt
	s_nop 1
	v_mov_b32_e32 v20, v124
	v_mov_b32_e32 v21, v125
	v_mov_b32_e32 v22, v126
	v_mov_b32_e32 v23, v127
	v_mov_b32_e32 v24, v128
	v_mov_b32_e32 v25, v129
	v_mov_b32_e32 v26, v130
	v_mov_b32_e32 v27, v131
	v_pk_fma_f32 v[16:17], v[16:17], v[20:21], v[24:25]
	v_pk_fma_f32 v[18:19], v[18:19], v[22:23], v[26:27]
	global_store_dwordx4 v[70:71], v[16:19], off offset:3072 nt
	s_nop 1
	v_mov_b32_e32 v16, v132
	v_mov_b32_e32 v17, v133
	v_mov_b32_e32 v18, v134
	v_mov_b32_e32 v19, v135
	v_mov_b32_e32 v20, v136
	v_mov_b32_e32 v21, v137
	v_mov_b32_e32 v22, v138
	v_mov_b32_e32 v23, v139
	v_add_co_u32_e32 v24, vcc, s12, v70
	v_pk_fma_f32 v[8:9], v[8:9], v[16:17], v[20:21]
	v_addc_co_u32_e32 v25, vcc, 0, v71, vcc
	v_pk_fma_f32 v[10:11], v[10:11], v[18:19], v[22:23]
	global_store_dwordx4 v[24:25], v[8:11], off nt
	s_nop 1
	v_mov_b32_e32 v8, v140
	v_mov_b32_e32 v9, v141
	v_mov_b32_e32 v10, v142
	v_mov_b32_e32 v11, v143
	v_mov_b32_e32 v16, v144
	v_mov_b32_e32 v17, v145
	v_mov_b32_e32 v18, v146
	v_mov_b32_e32 v19, v147
	v_pk_fma_f32 v[8:9], v[12:13], v[8:9], v[16:17]
	v_pk_fma_f32 v[10:11], v[14:15], v[10:11], v[18:19]
	global_store_dwordx4 v[24:25], v[8:11], off offset:1024 nt
	s_nop 1
	v_mov_b32_e32 v8, v148
	v_mov_b32_e32 v9, v149
	v_mov_b32_e32 v10, v150
	v_mov_b32_e32 v11, v151
	v_mov_b32_e32 v12, v152
	v_mov_b32_e32 v13, v153
	v_mov_b32_e32 v14, v154
	v_mov_b32_e32 v15, v155
	v_pk_fma_f32 v[4:5], v[4:5], v[8:9], v[12:13]
	v_pk_fma_f32 v[6:7], v[6:7], v[10:11], v[14:15]
	global_store_dwordx4 v[24:25], v[4:7], off offset:2048 nt
	s_nop 1
	v_mov_b32_e32 v4, v156
	v_mov_b32_e32 v5, v157
	v_mov_b32_e32 v6, v158
	v_mov_b32_e32 v7, v159
	v_mov_b32_e32 v8, v160
	v_mov_b32_e32 v9, v161
	v_mov_b32_e32 v10, v162
	v_mov_b32_e32 v11, v163
	v_pk_fma_f32 v[0:1], v[0:1], v[4:5], v[8:9]
	v_pk_fma_f32 v[2:3], v[2:3], v[6:7], v[10:11]
	global_store_dwordx4 v[24:25], v[0:3], off offset:3072 nt
	s_nop 1
	s_branch .LBB0_1181
